# rwkv_prep/readout loops: one LDS wait per four quads
# baseline (speedup 1.0000x reference)
.LBB0_707:
	v_mov_b32_e32 v94, s2
	s_waitcnt lgkmcnt(12)
	v_pk_mul_f32 v[90:91], v[136:137], v[6:7]
	v_pk_fma_f32 v[90:91], v[138:139], v[8:9], v[90:91]
	ds_read_b128 v[136:139], v94 offset:512
	v_pk_mul_f32 v[92:93], v[140:141], v[56:57]
	v_pk_fma_f32 v[92:93], v[142:143], v[58:59], v[92:93]
	ds_read_b128 v[140:143], v94 offset:640
	v_pk_fma_f32 v[90:91], v[144:145], v[10:11], v[90:91]
	v_pk_fma_f32 v[90:91], v[146:147], v[12:13], v[90:91]
	ds_read_b128 v[144:147], v94 offset:528
	v_pk_fma_f32 v[92:93], v[148:149], v[60:61], v[92:93]
	v_pk_fma_f32 v[92:93], v[150:151], v[62:63], v[92:93]
	ds_read_b128 v[148:151], v94 offset:656
	s_waitcnt lgkmcnt(12)
	v_pk_fma_f32 v[90:91], v[152:153], v[14:15], v[90:91]
	v_pk_fma_f32 v[90:91], v[154:155], v[16:17], v[90:91]
	ds_read_b128 v[152:155], v94 offset:544
	v_pk_fma_f32 v[92:93], v[156:157], v[64:65], v[92:93]
	v_pk_fma_f32 v[92:93], v[158:159], v[66:67], v[92:93]
	ds_read_b128 v[156:159], v94 offset:672
	v_pk_fma_f32 v[90:91], v[160:161], v[18:19], v[90:91]
	v_pk_fma_f32 v[90:91], v[162:163], v[20:21], v[90:91]
	ds_read_b128 v[160:163], v94 offset:560
	v_pk_fma_f32 v[92:93], v[164:165], v[68:69], v[92:93]
	v_pk_fma_f32 v[92:93], v[166:167], v[70:71], v[92:93]
	ds_read_b128 v[164:167], v94 offset:688
	s_waitcnt lgkmcnt(12)
	v_pk_fma_f32 v[90:91], v[184:185], v[22:23], v[90:91]
	v_pk_fma_f32 v[90:91], v[186:187], v[24:25], v[90:91]
	ds_read_b128 v[184:187], v94 offset:576
	v_pk_fma_f32 v[92:93], v[188:189], v[72:73], v[92:93]
	v_pk_fma_f32 v[92:93], v[190:191], v[74:75], v[92:93]
	ds_read_b128 v[188:191], v94 offset:704
	v_pk_fma_f32 v[90:91], v[192:193], v[26:27], v[90:91]
	v_pk_fma_f32 v[90:91], v[194:195], v[28:29], v[90:91]
	ds_read_b128 v[192:195], v94 offset:592
	v_pk_fma_f32 v[92:93], v[196:197], v[76:77], v[92:93]
	v_pk_fma_f32 v[92:93], v[198:199], v[78:79], v[92:93]
	ds_read_b128 v[196:199], v94 offset:720
	s_waitcnt lgkmcnt(12)
	v_pk_fma_f32 v[90:91], v[200:201], v[30:31], v[90:91]
	v_pk_fma_f32 v[90:91], v[202:203], v[32:33], v[90:91]
	ds_read_b128 v[200:203], v94 offset:608
	v_pk_fma_f32 v[92:93], v[212:213], v[80:81], v[92:93]
	v_pk_fma_f32 v[92:93], v[214:215], v[82:83], v[92:93]
	ds_read_b128 v[212:215], v94 offset:736
	v_pk_fma_f32 v[90:91], v[216:217], v[34:35], v[90:91]
	v_pk_fma_f32 v[90:91], v[218:219], v[36:37], v[90:91]
	ds_read_b128 v[216:219], v94 offset:624
	v_pk_fma_f32 v[92:93], v[220:221], v[84:85], v[92:93]
	v_pk_fma_f32 v[92:93], v[222:223], v[86:87], v[92:93]
	ds_read_b128 v[220:223], v94 offset:752
	s_addk_i32 s2, 0x200
	v_add_f32_e32 v98, v90, v88
	v_add_f32_e32 v99, v92, v89
	v_add_f32_e32 v98, v98, v91
	v_add_f32_e32 v99, v99, v93
	v_mul_f32_e32 v98, 0xbfb8aa3b, v98
	v_mul_f32_e32 v99, 0xbfb8aa3b, v99
	v_exp_f32_e32 v98, v98
	v_exp_f32_e32 v99, v99
	s_nop 0
	v_add_f32_e32 v98, 1.0, v98
	v_add_f32_e32 v99, 1.0, v99
	v_rcp_f32_e32 v98, v98
	v_rcp_f32_e32 v99, v99
	s_nop 0
	v_mul_f32_e32 v98, 0xbf60028a, v98
	v_mul_f32_e32 v99, 0xbf60028a, v99
	v_exp_f32_e32 v98, v98
	v_exp_f32_e32 v99, v99
	s_cmpk_eq_i32 s2, 0x4400
	s_nop 0
	global_store_dword v95, v98, s[14:15]
	global_store_dword v95, v99, s[16:17]
	v_add_u32_e32 v95, 0x400, v95
	s_cbranch_scc0 .LBB0_707
	s_waitcnt lgkmcnt(0)
	v_lshlrev_b64 v[6:7], 2, v[2:3]
	v_lshl_add_u64 v[66:67], s[68:69], 0, v[6:7]
	v_mov_b32_e32 v96, v6
	global_load_dword v8, v96, s[68:69]
	global_load_dword v9, v96, s[68:69] offset:1024
	global_load_dword v10, v96, s[68:69] offset:2048
	global_load_dword v11, v96, s[68:69] offset:3072
	v_add_u32_e32 v96, 0x1000, v96
	global_load_dword v12, v96, s[68:69]
	global_load_dword v13, v96, s[68:69] offset:1024
	global_load_dword v14, v96, s[68:69] offset:2048
	global_load_dword v15, v96, s[68:69] offset:3072
	v_add_u32_e32 v96, 0x1000, v96
	global_load_dword v16, v96, s[68:69]
	global_load_dword v17, v96, s[68:69] offset:1024
	global_load_dword v18, v96, s[68:69] offset:2048
	global_load_dword v19, v96, s[68:69] offset:3072
	v_add_u32_e32 v96, 0x1000, v96
	global_load_dword v20, v96, s[68:69]
	global_load_dword v21, v96, s[68:69] offset:1024
	global_load_dword v22, v96, s[68:69] offset:2048
	global_load_dword v23, v96, s[68:69] offset:3072
	v_add_u32_e32 v96, 0x1000, v96
	global_load_dword v24, v96, s[68:69]
	global_load_dword v25, v96, s[68:69] offset:1024
	global_load_dword v26, v96, s[68:69] offset:2048
	global_load_dword v27, v96, s[68:69] offset:3072
	v_add_u32_e32 v96, 0x1000, v96
	global_load_dword v28, v96, s[68:69]
	global_load_dword v29, v96, s[68:69] offset:1024
	global_load_dword v30, v96, s[68:69] offset:2048
	global_load_dword v31, v96, s[68:69] offset:3072
	v_add_u32_e32 v96, 0x1000, v96
	global_load_dword v32, v96, s[68:69]
	global_load_dword v33, v96, s[68:69] offset:1024
	global_load_dword v34, v96, s[68:69] offset:2048
	global_load_dword v35, v96, s[68:69] offset:3072
	v_add_u32_e32 v96, 0x1000, v96
	global_load_dword v36, v96, s[68:69]
	global_load_dword v37, v96, s[68:69] offset:1024
	global_load_dword v38, v96, s[68:69] offset:2048
	global_load_dword v39, v96, s[68:69] offset:3072
	v_add_u32_e32 v96, 0x1000, v96
	global_load_dword v56, v96, s[68:69]
	global_load_dword v57, v96, s[68:69] offset:1024
	global_load_dword v58, v96, s[68:69] offset:2048
	global_load_dword v59, v96, s[68:69] offset:3072
	v_add_u32_e32 v96, 0x1000, v96
	global_load_dword v60, v96, s[68:69]
	global_load_dword v61, v96, s[68:69] offset:1024
	global_load_dword v62, v96, s[68:69] offset:2048
	global_load_dword v63, v96, s[68:69] offset:3072
	v_add_u32_e32 v96, 0x1000, v96
	global_load_dword v64, v96, s[68:69]
	global_load_dword v65, v96, s[68:69] offset:1024
	global_load_dword v66, v96, s[68:69] offset:2048
	global_load_dword v67, v96, s[68:69] offset:3072
	v_add_u32_e32 v96, 0x1000, v96
	global_load_dword v68, v96, s[68:69]
	global_load_dword v69, v96, s[68:69] offset:1024
	global_load_dword v70, v96, s[68:69] offset:2048
	global_load_dword v71, v96, s[68:69] offset:3072
	v_add_u32_e32 v96, 0x1000, v96
	global_load_dword v72, v96, s[68:69]
	global_load_dword v73, v96, s[68:69] offset:1024
	global_load_dword v74, v96, s[68:69] offset:2048
	global_load_dword v75, v96, s[68:69] offset:3072
	v_add_u32_e32 v96, 0x1000, v96
	global_load_dword v76, v96, s[68:69]
	global_load_dword v77, v96, s[68:69] offset:1024
	global_load_dword v78, v96, s[68:69] offset:2048
	global_load_dword v79, v96, s[68:69] offset:3072
	v_add_u32_e32 v96, 0x1000, v96
	global_load_dword v80, v96, s[68:69]
	global_load_dword v81, v96, s[68:69] offset:1024
	global_load_dword v82, v96, s[68:69] offset:2048
	global_load_dword v83, v96, s[68:69] offset:3072
	v_add_u32_e32 v96, 0x1000, v96
	global_load_dword v84, v96, s[68:69]
	global_load_dword v85, v96, s[68:69] offset:1024
	global_load_dword v86, v96, s[68:69] offset:2048
	global_load_dword v87, v96, s[68:69] offset:3072
	s_mov_b32 s0, 0xc000
	v_readlane_b32 s44, v210, 18
	s_nop 0
	s_nop 0
	s_nop 0
	v_readlane_b32 s52, v210, 26
	s_nop 0
	s_nop 0
	s_nop 0
	v_readlane_b32 s53, v210, 27
	s_nop 0
	s_nop 0
	s_nop 0
	v_lshl_add_u64 v[4:5], v[4:5], 2, s[52:53]
	s_nop 0
	s_nop 0
	s_nop 0
	s_movk_i32 s0, 0x5000
	s_nop 0
	s_mov_b32 s0, 0xd000
	s_nop 0
	s_movk_i32 s0, 0x6000
	s_nop 0
	s_mov_b32 s0, 0xe000
	s_nop 0
	s_movk_i32 s0, 0x7000
	s_nop 0
	s_mov_b32 s0, 0xf000
	s_nop 0
	s_nop 0
	s_nop 0
	s_nop 0
	s_nop 0
	s_nop 0
	s_nop 0
	s_nop 0
	s_nop 0
	s_nop 0
	s_nop 0
	s_nop 0
	global_load_dword v88, v[4:5], off
	global_load_dword v89, v[4:5], off offset:1024
	v_and_b32_e32 v5, 63, v2
	v_ashrrev_i32_e32 v4, 6, v2
	v_readlane_b32 s56, v210, 30
	v_readlane_b32 s57, v210, 31
	v_readlane_b32 s58, v210, 32
	v_readlane_b32 s59, v210, 33
	v_cmp_eq_u32_e32 vcc, 0, v5
	v_ashrrev_i32_e32 v5, 31, v4
	v_readlane_b32 s80, v208, 27
	s_movk_i32 s61, 0x4000
	s_mov_b32 s6, 0
	v_lshl_add_u64 v[4:5], v[4:5], 2, s[24:25]
	v_lshl_add_u64 v[6:7], s[12:13], 0, v[6:7]
	s_movk_i32 s7, 0x100
	v_readlane_b32 s81, v208, 28
	v_readlane_b32 s82, v208, 29
	v_readlane_b32 s83, v208, 30
	v_readlane_b32 s84, v208, 31
	v_readlane_b32 s85, v208, 32
	v_readlane_b32 s86, v208, 33
	v_readlane_b32 s87, v208, 34
	v_readlane_b32 s88, v208, 35
	v_readlane_b32 s89, v208, 36
	v_readlane_b32 s90, v208, 37
	v_readlane_b32 s91, v208, 38
	v_readlane_b32 s92, v208, 39
	v_readlane_b32 s93, v208, 40
	v_readlane_b32 s94, v208, 41
	v_readlane_b32 s95, v208, 42
	s_mov_b32 s56, 0x10000
	s_mov_b32 s57, 0x20000
	s_mov_b32 s58, 0x30000
	s_movk_i32 s59, 0x70
	v_readlane_b32 s45, v210, 19
	v_readlane_b32 s46, v210, 20
	v_readlane_b32 s47, v210, 21
	v_readlane_b32 s48, v210, 22
	v_readlane_b32 s49, v210, 23
	v_readlane_b32 s50, v210, 24
	v_readlane_b32 s51, v210, 25
	v_readlane_b32 s54, v210, 28
	v_readlane_b32 s55, v210, 29
	s_waitcnt vmcnt(0) lgkmcnt(0)
	v_mov_b32_e32 v94, s7
	ds_read_b128 v[136:139], v94 offset:0
	ds_read_b128 v[140:143], v94 offset:128
	ds_read_b128 v[144:147], v94 offset:16
	ds_read_b128 v[148:151], v94 offset:144
	ds_read_b128 v[152:155], v94 offset:32
	ds_read_b128 v[156:159], v94 offset:160
	ds_read_b128 v[160:163], v94 offset:48
	ds_read_b128 v[164:167], v94 offset:176
	ds_read_b128 v[184:187], v94 offset:64
	ds_read_b128 v[188:191], v94 offset:192
	ds_read_b128 v[192:195], v94 offset:80
	ds_read_b128 v[196:199], v94 offset:208
	ds_read_b128 v[200:203], v94 offset:96
	ds_read_b128 v[212:215], v94 offset:224
	ds_read_b128 v[216:219], v94 offset:112
	ds_read_b128 v[220:223], v94 offset:240
	s_lshl_b32 s4, s97, 10
	v_lshlrev_b32_e32 v95, 2, v2
	v_add_u32_e32 v95, s4, v95
	s_mov_b32 s1, 0
	v_mad_i64_i32 v[44:45], s[2:3], s97, v178, v[6:7]
	global_load_dword v42, v[44:45], off
	global_load_dword v43, v[44:45], off offset:1024
.LBB0_710:
	v_mov_b32_e32 v94, s7
	s_add_i32 s0, s97, s6
	s_waitcnt vmcnt(0)
	v_mul_f32_e32 v97, v0, v43
	v_mul_f32_e32 v102, v97, v97
	s_waitcnt lgkmcnt(12)
	v_pk_mul_f32 v[90:91], v[136:137], v[8:9]
	v_pk_fma_f32 v[90:91], v[138:139], v[10:11], v[90:91]
	ds_read_b128 v[136:139], v94 offset:512
	v_add_f32_dpp v102, v102, v102 quad_perm:[1,0,3,2] row_mask:0xf bank_mask:0xf bound_ctrl:1
	v_pk_mul_f32 v[92:93], v[140:141], v[56:57]
	v_pk_fma_f32 v[92:93], v[142:143], v[58:59], v[92:93]
	ds_read_b128 v[140:143], v94 offset:640
	v_add_f32_dpp v102, v102, v102 quad_perm:[2,3,0,1] row_mask:0xf bank_mask:0xf bound_ctrl:1
	v_pk_fma_f32 v[90:91], v[144:145], v[12:13], v[90:91]
	v_pk_fma_f32 v[90:91], v[146:147], v[14:15], v[90:91]
	ds_read_b128 v[144:147], v94 offset:528
	v_add_f32_dpp v102, v102, v102 row_half_mirror row_mask:0xf bank_mask:0xf bound_ctrl:1
	v_pk_fma_f32 v[92:93], v[148:149], v[60:61], v[92:93]
	v_pk_fma_f32 v[92:93], v[150:151], v[62:63], v[92:93]
	ds_read_b128 v[148:151], v94 offset:656
	v_add_f32_dpp v102, v102, v102 row_mirror row_mask:0xf bank_mask:0xf bound_ctrl:1
	s_waitcnt lgkmcnt(12)
	v_pk_fma_f32 v[90:91], v[152:153], v[16:17], v[90:91]
	v_pk_fma_f32 v[90:91], v[154:155], v[18:19], v[90:91]
	ds_read_b128 v[152:155], v94 offset:544
	v_add_f32_dpp v102, v102, v102 row_bcast:15 row_mask:0xa bank_mask:0xf
	v_pk_fma_f32 v[92:93], v[156:157], v[64:65], v[92:93]
	v_pk_fma_f32 v[92:93], v[158:159], v[66:67], v[92:93]
	ds_read_b128 v[156:159], v94 offset:672
	v_add_f32_dpp v102, v102, v102 row_bcast:31 row_mask:0xc bank_mask:0xf
	v_pk_fma_f32 v[90:91], v[160:161], v[20:21], v[90:91]
	v_pk_fma_f32 v[90:91], v[162:163], v[22:23], v[90:91]
	ds_read_b128 v[160:163], v94 offset:560
	v_pk_fma_f32 v[92:93], v[164:165], v[68:69], v[92:93]
	v_pk_fma_f32 v[92:93], v[166:167], v[70:71], v[92:93]
	ds_read_b128 v[164:167], v94 offset:688
	s_waitcnt lgkmcnt(12)
	v_pk_fma_f32 v[90:91], v[184:185], v[24:25], v[90:91]
	v_pk_fma_f32 v[90:91], v[186:187], v[26:27], v[90:91]
	ds_read_b128 v[184:187], v94 offset:576
	v_readlane_b32 s8, v102, 63
	v_pk_fma_f32 v[92:93], v[188:189], v[72:73], v[92:93]
	v_pk_fma_f32 v[92:93], v[190:191], v[74:75], v[92:93]
	ds_read_b128 v[188:191], v94 offset:704
	v_pk_fma_f32 v[90:91], v[192:193], v[28:29], v[90:91]
	v_pk_fma_f32 v[90:91], v[194:195], v[30:31], v[90:91]
	ds_read_b128 v[192:195], v94 offset:592
	v_pk_fma_f32 v[92:93], v[196:197], v[76:77], v[92:93]
	v_pk_fma_f32 v[92:93], v[198:199], v[78:79], v[92:93]
	ds_read_b128 v[196:199], v94 offset:720
	s_waitcnt lgkmcnt(12)
	v_pk_fma_f32 v[90:91], v[200:201], v[32:33], v[90:91]
	v_pk_fma_f32 v[90:91], v[202:203], v[34:35], v[90:91]
	ds_read_b128 v[200:203], v94 offset:608
	v_pk_fma_f32 v[92:93], v[212:213], v[80:81], v[92:93]
	v_pk_fma_f32 v[92:93], v[214:215], v[82:83], v[92:93]
	ds_read_b128 v[212:215], v94 offset:736
	v_pk_fma_f32 v[90:91], v[216:217], v[36:37], v[90:91]
	v_pk_fma_f32 v[90:91], v[218:219], v[38:39], v[90:91]
	ds_read_b128 v[216:219], v94 offset:624
	v_pk_fma_f32 v[92:93], v[220:221], v[84:85], v[92:93]
	v_pk_fma_f32 v[92:93], v[222:223], v[86:87], v[92:93]
	ds_read_b128 v[220:223], v94 offset:752
	v_add_f32_e32 v98, v90, v88
	v_add_f32_e32 v99, v92, v89
	v_add_f32_e32 v98, v98, v91
	v_add_f32_e32 v99, v99, v93
	v_mul_f32_e32 v98, 0xbfb8aa3b, v98
	v_mul_f32_e32 v99, 0xbfb8aa3b, v99
	v_exp_f32_e32 v98, v98
	v_exp_f32_e32 v99, v99
	v_mov_b32_e32 v103, s8
	v_add_f32_e32 v98, 1.0, v98
	v_add_f32_e32 v99, 1.0, v99
	v_rcp_f32_e32 v98, v98
	v_rcp_f32_e32 v99, v99
	v_max_f32_e32 v103, 0x179abe15, v103
	v_rsq_f32_e32 v103, v103
	v_add_f32_e32 v112, -1.0, v98
	v_add_f32_e32 v113, -1.0, v99
	v_fma_f32 v112, v54, v112, 1.0
	v_fma_f32 v113, v54, v113, 1.0
	v_mul_f32_e32 v112, v43, v112
	v_fmac_f32_e32 v112, v43, v113
	v_mul_f32_e32 v97, v97, v103
	v_mul_f32_e32 v112, v42, v112
	v_mul_f32_e32 v114, v55, v112
	global_store_dword v95, v98, s[18:19]
	global_store_dword v95, v99, s[20:21]
	v_add_f32_dpp v114, v114, v114 quad_perm:[1,0,3,2] row_mask:0xf bank_mask:0xf bound_ctrl:1
	global_store_dword v95, v97, s[22:23]
	s_add_i32 s8, s0, 1
	v_add_f32_dpp v114, v114, v114 quad_perm:[2,3,0,1] row_mask:0xf bank_mask:0xf bound_ctrl:1
	s_cmp_eq_u32 s6, 33
	s_cbranch_scc1 .Lrw2_noload
	v_mad_i64_i32 v[44:45], s[2:3], s8, v178, v[6:7]
	global_load_dword v42, v[44:45], off
	global_load_dword v43, v[44:45], off offset:1024

.LBB0_1129:
	v_mov_b32_e32 v94, s4
	s_waitcnt vmcnt(0)
	v_add_f32_e32 v88, v84, v85
	v_mul_f32_e32 v86, v86, v87
	v_mov_b32_e32 v89, v88
	s_waitcnt lgkmcnt(12)
	v_pk_mul_f32 v[92:93], v[136:137], v[2:3]
	v_pk_fma_f32 v[92:93], v[138:139], v[4:5], v[92:93]
	ds_read_b128 v[136:139], v94 offset:256
	v_add_f32_dpp v89, v89, v89 quad_perm:[1,0,3,2] row_mask:0xf bank_mask:0xf bound_ctrl:1
	v_pk_fma_f32 v[92:93], v[140:141], v[6:7], v[92:93]
	v_pk_fma_f32 v[92:93], v[142:143], v[8:9], v[92:93]
	ds_read_b128 v[140:143], v94 offset:272
	v_add_f32_dpp v89, v89, v89 quad_perm:[2,3,0,1] row_mask:0xf bank_mask:0xf bound_ctrl:1
	v_pk_fma_f32 v[92:93], v[144:145], v[10:11], v[92:93]
	v_pk_fma_f32 v[92:93], v[146:147], v[12:13], v[92:93]
	ds_read_b128 v[144:147], v94 offset:288
	v_add_f32_dpp v89, v89, v89 row_half_mirror row_mask:0xf bank_mask:0xf bound_ctrl:1
	v_pk_fma_f32 v[92:93], v[148:149], v[14:15], v[92:93]
	v_pk_fma_f32 v[92:93], v[150:151], v[16:17], v[92:93]
	ds_read_b128 v[148:151], v94 offset:304
	v_add_f32_dpp v89, v89, v89 row_mirror row_mask:0xf bank_mask:0xf bound_ctrl:1
	s_waitcnt lgkmcnt(12)
	v_pk_fma_f32 v[92:93], v[152:153], v[18:19], v[92:93]
	v_pk_fma_f32 v[92:93], v[154:155], v[20:21], v[92:93]
	ds_read_b128 v[152:155], v94 offset:320
	v_add_f32_dpp v89, v89, v89 row_bcast:15 row_mask:0xa bank_mask:0xf
	v_pk_fma_f32 v[92:93], v[156:157], v[22:23], v[92:93]
	v_pk_fma_f32 v[92:93], v[158:159], v[24:25], v[92:93]
	ds_read_b128 v[156:159], v94 offset:336
	v_add_f32_dpp v89, v89, v89 row_bcast:31 row_mask:0xc bank_mask:0xf
	v_pk_fma_f32 v[92:93], v[160:161], v[26:27], v[92:93]
	v_pk_fma_f32 v[92:93], v[162:163], v[28:29], v[92:93]
	ds_read_b128 v[160:163], v94 offset:352
	v_readlane_b32 s5, v89, 63
	v_pk_fma_f32 v[92:93], v[164:165], v[30:31], v[92:93]
	v_pk_fma_f32 v[92:93], v[166:167], v[32:33], v[92:93]
	ds_read_b128 v[164:167], v94 offset:368
	v_mov_b32_e32 v89, s5
	v_fmac_f32_e32 v88, 0xbc800000, v89
	s_waitcnt lgkmcnt(12)
	v_pk_fma_f32 v[92:93], v[184:185], v[34:35], v[92:93]
	v_pk_fma_f32 v[92:93], v[186:187], v[36:37], v[92:93]
	ds_read_b128 v[184:187], v94 offset:384
	v_mul_f32_e32 v90, v88, v88
	v_pk_fma_f32 v[92:93], v[188:189], v[38:39], v[92:93]
	v_pk_fma_f32 v[92:93], v[190:191], v[40:41], v[92:93]
	ds_read_b128 v[188:191], v94 offset:400
	v_add_f32_dpp v90, v90, v90 quad_perm:[1,0,3,2] row_mask:0xf bank_mask:0xf bound_ctrl:1
	v_pk_fma_f32 v[92:93], v[192:193], v[58:59], v[92:93]
	v_pk_fma_f32 v[92:93], v[194:195], v[60:61], v[92:93]
	ds_read_b128 v[192:195], v94 offset:416
	v_add_f32_dpp v90, v90, v90 quad_perm:[2,3,0,1] row_mask:0xf bank_mask:0xf bound_ctrl:1
	v_pk_fma_f32 v[92:93], v[196:197], v[62:63], v[92:93]
	v_pk_fma_f32 v[92:93], v[198:199], v[64:65], v[92:93]
	ds_read_b128 v[196:199], v94 offset:432
	v_add_f32_dpp v90, v90, v90 row_half_mirror row_mask:0xf bank_mask:0xf bound_ctrl:1
	s_waitcnt lgkmcnt(12)
	v_pk_fma_f32 v[92:93], v[200:201], v[66:67], v[92:93]
	v_pk_fma_f32 v[92:93], v[202:203], v[68:69], v[92:93]
	ds_read_b128 v[200:203], v94 offset:448
	v_add_f32_dpp v90, v90, v90 row_mirror row_mask:0xf bank_mask:0xf bound_ctrl:1
	v_pk_fma_f32 v[92:93], v[212:213], v[70:71], v[92:93]
	v_pk_fma_f32 v[92:93], v[214:215], v[72:73], v[92:93]
	ds_read_b128 v[212:215], v94 offset:464
	v_add_f32_dpp v90, v90, v90 row_bcast:15 row_mask:0xa bank_mask:0xf
	v_pk_fma_f32 v[92:93], v[216:217], v[74:75], v[92:93]
	v_pk_fma_f32 v[92:93], v[218:219], v[76:77], v[92:93]
	ds_read_b128 v[216:219], v94 offset:480
	v_add_f32_dpp v90, v90, v90 row_bcast:31 row_mask:0xc bank_mask:0xf
	v_pk_fma_f32 v[92:93], v[220:221], v[78:79], v[92:93]
	v_pk_fma_f32 v[92:93], v[222:223], v[80:81], v[92:93]
	ds_read_b128 v[220:223], v94 offset:496
	s_nop 1
	v_readlane_b32 s5, v90, 63
	v_add_f32_e32 v94, v92, v93
	v_mov_b32_e32 v95, s5
	v_fmamk_f32 v95, v95, 0x3c800000, v176
	v_rsq_f32_e32 v95, v95
	v_mul_f32_e32 v88, v88, v82
	s_addk_i32 s4, 0x100
	v_fma_f32 v88, v88, v95, v83
	v_add_f32_e32 v88, v88, v86
	v_mul_f32_e32 v88, v88, v94
	v_cvt_pk_bf16_f32 v88, v88, s0
	s_mov_b64 s[38:39], 0x800
	global_store_short v[48:49], v88, off
	v_lshl_add_u64 v[48:49], v[48:49], 0, s[38:39]
	s_cmpk_eq_i32 s4, 0x2200
	s_cbranch_scc1 .Lro_done
	v_lshl_add_u64 v[94:95], v[54:55], 0, s[2:3]
	global_load_dword v84, v[94:95], off
	v_lshl_add_u64 v[94:95], v[56:57], 0, s[2:3]
	global_load_dword v85, v[94:95], off
	global_load_dword v86, v[52:53], off
	global_load_dword v87, v[50:51], off
	s_add_u32 s2, s2, 0x400
	s_addc_u32 s3, s3, 0
	v_lshl_add_u64 v[52:53], v[52:53], 0, 16
	v_lshl_add_u64 v[50:51], v[50:51], 0, s[36:37]
	s_branch .LBB0_1129
